# saddr-form LDS-DMA loads in proj/gate-up K-loops on top of cached row scales + wait skipping + early L1 inv
# speedup vs baseline: 1.0165x; 1.0039x over previous
.LBB0_342:
	s_add_u32 s33, s44, 0xfff80080
	s_addc_u32 s43, s45, -1
	s_add_i32 s50, 0, 0x10000
	s_cmp_eq_u32 s35, 28
	s_cselect_b32 s49, s27, s43
	s_cselect_b32 s48, s28, s33
	v_add_u32_e32 v142, s50, v149
	s_cselect_b32 s47, s25, s34
	s_cselect_b32 s46, s29, s31
	s_add_i32 s33, 0, 0x14000
	ds_read_b128 v[154:157], v142
	ds_read_b128 v[168:171], v142 offset:1024
	ds_read_b128 v[172:175], v142 offset:2048
	ds_read_b128 v[176:179], v142 offset:3072
	v_add_u32_e32 v142, s33, v149
	ds_read_b128 v[180:183], v142
	ds_read_b128 v[184:187], v142 offset:1024
	ds_read_b128 v[188:191], v142 offset:2048
	ds_read_b128 v[192:195], v142 offset:3072
	s_add_i32 m0, s12, 0xc000
	ds_read_b128 v[196:199], v167
	ds_read_b128 v[200:203], v167 offset:1024
	ds_read_b128 v[204:207], v167 offset:2048
	ds_read_b128 v[208:211], v167 offset:3072
	ds_read_b128 v[212:215], v167 offset:4096
	ds_read_b128 v[216:219], v167 offset:5120
	ds_read_b128 v[220:223], v167 offset:6144
	ds_read_b128 v[224:227], v167 offset:7168
	global_load_lds_dwordx4 v140, s[44:45]
	s_add_i32 m0, s12, 0xe000
	s_nop 0
	global_load_lds_dwordx4 v138, s[44:45]
	s_cmp_lg_u32 s32, 0
	s_cbranch_scc1 .Lpj_skip1
	s_waitcnt vmcnt(8)
.Lpj_skip1:
	s_waitcnt lgkmcnt(0)
	s_barrier
	s_setprio 1
	s_waitcnt lgkmcnt(0)
	v_mfma_f32_16x16x32_bf16 v[128:131], v[154:157], v[196:199], v[128:131]
	v_mfma_f32_16x16x32_bf16 v[124:127], v[172:175], v[196:199], v[124:127]
	v_mfma_f32_16x16x32_bf16 v[116:119], v[154:157], v[204:207], v[116:119]
	v_mfma_f32_16x16x32_bf16 v[108:111], v[172:175], v[204:207], v[108:111]
	v_mfma_f32_16x16x32_bf16 v[100:103], v[154:157], v[212:215], v[100:103]
	v_mfma_f32_16x16x32_bf16 v[92:95], v[172:175], v[212:215], v[92:95]
	v_mfma_f32_16x16x32_bf16 v[84:87], v[154:157], v[220:223], v[84:87]
	v_mfma_f32_16x16x32_bf16 v[76:79], v[172:175], v[220:223], v[76:79]
	v_mfma_f32_16x16x32_bf16 v[128:131], v[168:171], v[200:203], v[128:131]
	v_mfma_f32_16x16x32_bf16 v[124:127], v[176:179], v[200:203], v[124:127]
	v_mfma_f32_16x16x32_bf16 v[116:119], v[168:171], v[208:211], v[116:119]
	v_mfma_f32_16x16x32_bf16 v[108:111], v[176:179], v[208:211], v[108:111]
	v_mfma_f32_16x16x32_bf16 v[100:103], v[168:171], v[216:219], v[100:103]
	v_mfma_f32_16x16x32_bf16 v[92:95], v[176:179], v[216:219], v[92:95]
	v_mfma_f32_16x16x32_bf16 v[84:87], v[168:171], v[224:227], v[84:87]
	v_mfma_f32_16x16x32_bf16 v[76:79], v[176:179], v[224:227], v[76:79]
	s_setprio 0
	s_setprio 1
	v_mfma_f32_16x16x32_bf16 v[120:123], v[180:183], v[196:199], v[120:123]
	v_mfma_f32_16x16x32_bf16 v[112:115], v[188:191], v[196:199], v[112:115]
	v_mfma_f32_16x16x32_bf16 v[104:107], v[180:183], v[204:207], v[104:107]
	v_mfma_f32_16x16x32_bf16 v[96:99], v[188:191], v[204:207], v[96:99]
	v_mfma_f32_16x16x32_bf16 v[88:91], v[180:183], v[212:215], v[88:91]
	v_mfma_f32_16x16x32_bf16 v[80:83], v[188:191], v[212:215], v[80:83]
	v_mfma_f32_16x16x32_bf16 v[72:75], v[180:183], v[220:223], v[72:75]
	v_mfma_f32_16x16x32_bf16 v[68:71], v[188:191], v[220:223], v[68:71]
	v_mfma_f32_16x16x32_bf16 v[120:123], v[184:187], v[200:203], v[120:123]
	v_mfma_f32_16x16x32_bf16 v[112:115], v[192:195], v[200:203], v[112:115]
	v_mfma_f32_16x16x32_bf16 v[104:107], v[184:187], v[208:211], v[104:107]
	v_mfma_f32_16x16x32_bf16 v[96:99], v[192:195], v[208:211], v[96:99]
	v_mfma_f32_16x16x32_bf16 v[88:91], v[184:187], v[216:219], v[88:91]
	v_mfma_f32_16x16x32_bf16 v[80:83], v[192:195], v[216:219], v[80:83]
	v_mfma_f32_16x16x32_bf16 v[72:75], v[184:187], v[224:227], v[72:75]
	v_mfma_f32_16x16x32_bf16 v[68:71], v[192:195], v[224:227], v[68:71]
	s_setprio 0
	s_barrier
	s_add_i32 s43, s50, s10
	s_mov_b32 m0, s43
	ds_read_b128 v[196:199], v167 offset:16384
	ds_read_b128 v[200:203], v167 offset:17408
	ds_read_b128 v[204:207], v167 offset:18432
	ds_read_b128 v[208:211], v167 offset:19456
	ds_read_b128 v[212:215], v167 offset:20480
	ds_read_b128 v[216:219], v167 offset:21504
	ds_read_b128 v[220:223], v167 offset:22528
	ds_read_b128 v[224:227], v167 offset:23552
	global_load_lds_dwordx4 v2, s[46:47]
	s_add_i32 m0, s43, 0x2000
	s_add_u32 s50, s46, 0x80000
	s_addc_u32 s51, s47, 0
	s_add_i32 s33, s33, s10
	global_load_lds_dwordx4 v0, s[46:47]
	s_mov_b32 m0, s33
	s_nop 0
	global_load_lds_dwordx4 v2, s[50:51]
	s_add_i32 m0, s33, 0x2000
	s_nop 0
	global_load_lds_dwordx4 v0, s[50:51]
	s_mov_b32 m0, s12
	s_nop 0
	global_load_lds_dwordx4 v134, s[48:49]
	s_mov_b32 m0, s13
	s_nop 0
	global_load_lds_dwordx4 v132, s[48:49]
	s_cmp_lg_u32 s32, 0
	s_cbranch_scc1 .Lpj_skip2
	s_waitcnt vmcnt(8)
.Lpj_skip2:
	s_mov_b32 s32, 0
	s_waitcnt lgkmcnt(0)
	s_barrier
	s_setprio 1
	s_waitcnt lgkmcnt(0)
	v_mfma_f32_16x16x32_bf16 v[64:67], v[154:157], v[196:199], v[64:67]
	v_mfma_f32_16x16x32_bf16 v[60:63], v[172:175], v[196:199], v[60:63]
	v_mfma_f32_16x16x32_bf16 v[52:55], v[154:157], v[204:207], v[52:55]
	v_mfma_f32_16x16x32_bf16 v[44:47], v[172:175], v[204:207], v[44:47]
	v_mfma_f32_16x16x32_bf16 v[36:39], v[154:157], v[212:215], v[36:39]
	v_mfma_f32_16x16x32_bf16 v[28:31], v[172:175], v[212:215], v[28:31]
	v_mfma_f32_16x16x32_bf16 v[20:23], v[154:157], v[220:223], v[20:23]
	v_mfma_f32_16x16x32_bf16 v[12:15], v[172:175], v[220:223], v[12:15]
	v_mfma_f32_16x16x32_bf16 v[64:67], v[168:171], v[200:203], v[64:67]
	v_mfma_f32_16x16x32_bf16 v[60:63], v[176:179], v[200:203], v[60:63]
	v_mfma_f32_16x16x32_bf16 v[52:55], v[168:171], v[208:211], v[52:55]
	v_mfma_f32_16x16x32_bf16 v[44:47], v[176:179], v[208:211], v[44:47]
	v_mfma_f32_16x16x32_bf16 v[36:39], v[168:171], v[216:219], v[36:39]
	v_mfma_f32_16x16x32_bf16 v[28:31], v[176:179], v[216:219], v[28:31]
	v_mfma_f32_16x16x32_bf16 v[20:23], v[168:171], v[224:227], v[20:23]
	v_mfma_f32_16x16x32_bf16 v[12:15], v[176:179], v[224:227], v[12:15]
	s_setprio 0
	s_setprio 1
	v_mfma_f32_16x16x32_bf16 v[56:59], v[180:183], v[196:199], v[56:59]
	v_mfma_f32_16x16x32_bf16 v[48:51], v[188:191], v[196:199], v[48:51]
	v_mfma_f32_16x16x32_bf16 v[40:43], v[180:183], v[204:207], v[40:43]
	v_mfma_f32_16x16x32_bf16 v[32:35], v[188:191], v[204:207], v[32:35]
	v_mfma_f32_16x16x32_bf16 v[24:27], v[180:183], v[212:215], v[24:27]
	v_mfma_f32_16x16x32_bf16 v[16:19], v[188:191], v[212:215], v[16:19]
	v_mfma_f32_16x16x32_bf16 v[8:11], v[180:183], v[220:223], v[8:11]
	v_mfma_f32_16x16x32_bf16 v[4:7], v[188:191], v[220:223], v[4:7]
	v_mfma_f32_16x16x32_bf16 v[56:59], v[184:187], v[200:203], v[56:59]
	v_mfma_f32_16x16x32_bf16 v[48:51], v[192:195], v[200:203], v[48:51]
	v_mfma_f32_16x16x32_bf16 v[40:43], v[184:187], v[208:211], v[40:43]
	v_mfma_f32_16x16x32_bf16 v[32:35], v[192:195], v[208:211], v[32:35]
	v_mfma_f32_16x16x32_bf16 v[24:27], v[184:187], v[216:219], v[24:27]
	v_mfma_f32_16x16x32_bf16 v[16:19], v[192:195], v[216:219], v[16:19]
	v_mfma_f32_16x16x32_bf16 v[8:11], v[184:187], v[224:227], v[8:11]
	v_mfma_f32_16x16x32_bf16 v[4:7], v[192:195], v[224:227], v[4:7]
	s_setprio 0
	s_barrier
	s_add_i32 s33, 0, 0x18000
	v_add_u32_e32 v144, s33, v149
	s_add_i32 s43, 0, 0x1c000
	ds_read_b128 v[154:157], v144
	ds_read_b128 v[168:171], v144 offset:1024
	ds_read_b128 v[172:175], v144 offset:2048
	ds_read_b128 v[176:179], v144 offset:3072
	v_add_u32_e32 v144, s43, v149
	ds_read_b128 v[180:183], v144
	ds_read_b128 v[184:187], v144 offset:1024
	ds_read_b128 v[188:191], v144 offset:2048
	ds_read_b128 v[192:195], v144 offset:3072
	s_add_u32 s48, s48, 0x80000
	s_addc_u32 s49, s49, 0
	s_mov_b32 m0, s14
	ds_read_b128 v[196:199], v167 offset:32768
	ds_read_b128 v[200:203], v167 offset:33792
	ds_read_b128 v[204:207], v167 offset:34816
	ds_read_b128 v[208:211], v167 offset:35840
	ds_read_b128 v[212:215], v167 offset:36864
	ds_read_b128 v[216:219], v167 offset:37888
	ds_read_b128 v[220:223], v167 offset:38912
	ds_read_b128 v[224:227], v167 offset:39936
	global_load_lds_dwordx4 v134, s[48:49]
	s_mov_b32 m0, s15
	s_nop 0
	global_load_lds_dwordx4 v132, s[48:49]
	s_waitcnt vmcnt(8)
	s_waitcnt lgkmcnt(0)
	s_barrier
	s_setprio 1
	s_waitcnt lgkmcnt(0)
	v_mfma_f32_16x16x32_bf16 v[128:131], v[154:157], v[196:199], v[128:131]
	v_mfma_f32_16x16x32_bf16 v[124:127], v[172:175], v[196:199], v[124:127]
	v_mfma_f32_16x16x32_bf16 v[116:119], v[154:157], v[204:207], v[116:119]
	v_mfma_f32_16x16x32_bf16 v[108:111], v[172:175], v[204:207], v[108:111]
	v_mfma_f32_16x16x32_bf16 v[100:103], v[154:157], v[212:215], v[100:103]
	v_mfma_f32_16x16x32_bf16 v[92:95], v[172:175], v[212:215], v[92:95]
	v_mfma_f32_16x16x32_bf16 v[84:87], v[154:157], v[220:223], v[84:87]
	v_mfma_f32_16x16x32_bf16 v[76:79], v[172:175], v[220:223], v[76:79]
	v_mfma_f32_16x16x32_bf16 v[128:131], v[168:171], v[200:203], v[128:131]
	v_mfma_f32_16x16x32_bf16 v[124:127], v[176:179], v[200:203], v[124:127]
	v_mfma_f32_16x16x32_bf16 v[116:119], v[168:171], v[208:211], v[116:119]
	v_mfma_f32_16x16x32_bf16 v[108:111], v[176:179], v[208:211], v[108:111]
	v_mfma_f32_16x16x32_bf16 v[100:103], v[168:171], v[216:219], v[100:103]
	v_mfma_f32_16x16x32_bf16 v[92:95], v[176:179], v[216:219], v[92:95]
	v_mfma_f32_16x16x32_bf16 v[84:87], v[168:171], v[224:227], v[84:87]
	v_mfma_f32_16x16x32_bf16 v[76:79], v[176:179], v[224:227], v[76:79]
	s_setprio 0
	s_setprio 1
	v_mfma_f32_16x16x32_bf16 v[120:123], v[180:183], v[196:199], v[120:123]
	v_mfma_f32_16x16x32_bf16 v[112:115], v[188:191], v[196:199], v[112:115]
	v_mfma_f32_16x16x32_bf16 v[104:107], v[180:183], v[204:207], v[104:107]
	v_mfma_f32_16x16x32_bf16 v[96:99], v[188:191], v[204:207], v[96:99]
	v_mfma_f32_16x16x32_bf16 v[88:91], v[180:183], v[212:215], v[88:91]
	v_mfma_f32_16x16x32_bf16 v[80:83], v[188:191], v[212:215], v[80:83]
	v_mfma_f32_16x16x32_bf16 v[72:75], v[180:183], v[220:223], v[72:75]
	v_mfma_f32_16x16x32_bf16 v[68:71], v[188:191], v[220:223], v[68:71]
	v_mfma_f32_16x16x32_bf16 v[120:123], v[184:187], v[200:203], v[120:123]
	v_mfma_f32_16x16x32_bf16 v[112:115], v[192:195], v[200:203], v[112:115]
	v_mfma_f32_16x16x32_bf16 v[104:107], v[184:187], v[208:211], v[104:107]
	v_mfma_f32_16x16x32_bf16 v[96:99], v[192:195], v[208:211], v[96:99]
	v_mfma_f32_16x16x32_bf16 v[88:91], v[184:187], v[216:219], v[88:91]
	v_mfma_f32_16x16x32_bf16 v[80:83], v[192:195], v[216:219], v[80:83]
	v_mfma_f32_16x16x32_bf16 v[72:75], v[184:187], v[224:227], v[72:75]
	v_mfma_f32_16x16x32_bf16 v[68:71], v[192:195], v[224:227], v[68:71]
	s_setprio 0
	s_barrier
	s_add_i32 s33, s33, s10
	s_mov_b32 m0, s33
	ds_read_b128 v[196:199], v167 offset:49152
	ds_read_b128 v[200:203], v167 offset:50176
	ds_read_b128 v[204:207], v167 offset:51200
	ds_read_b128 v[208:211], v167 offset:52224
	ds_read_b128 v[212:215], v167 offset:53248
	ds_read_b128 v[216:219], v167 offset:54272
	ds_read_b128 v[220:223], v167 offset:55296
	ds_read_b128 v[224:227], v167 offset:56320
	s_add_u32 s100, s46, 0x80
	s_addc_u32 s101, s47, 0
	global_load_lds_dwordx4 v2, s[100:101]
	s_add_i32 m0, s33, 0x2000
	s_add_u32 s46, s46, 0x80080
	s_addc_u32 s47, s47, 0
	s_add_i32 s33, s43, s10
	s_add_u32 s100, s46, 0xfff80000
	s_addc_u32 s101, s47, -1
	global_load_lds_dwordx4 v0, s[100:101]
	s_mov_b32 m0, s33
	s_nop 0
	global_load_lds_dwordx4 v2, s[46:47]
	s_add_i32 m0, s33, 0x2000
	s_nop 0
	global_load_lds_dwordx4 v0, s[46:47]
	s_mov_b32 m0, s16
	s_nop 0
	s_add_u32 s100, s48, 0xfff80080
	s_addc_u32 s101, s49, -1
	global_load_lds_dwordx4 v134, s[100:101]
	s_mov_b32 m0, s17
	s_nop 0
	s_add_u32 s100, s48, 0xfff80080
	s_addc_u32 s101, s49, -1
	global_load_lds_dwordx4 v132, s[100:101]
	s_waitcnt vmcnt(8)
	s_waitcnt lgkmcnt(0)
	s_barrier
	s_setprio 1
	s_waitcnt lgkmcnt(0)
	v_mfma_f32_16x16x32_bf16 v[64:67], v[154:157], v[196:199], v[64:67]
	v_mfma_f32_16x16x32_bf16 v[60:63], v[172:175], v[196:199], v[60:63]
	v_mfma_f32_16x16x32_bf16 v[52:55], v[154:157], v[204:207], v[52:55]
	v_mfma_f32_16x16x32_bf16 v[44:47], v[172:175], v[204:207], v[44:47]
	v_mfma_f32_16x16x32_bf16 v[36:39], v[154:157], v[212:215], v[36:39]
	v_mfma_f32_16x16x32_bf16 v[28:31], v[172:175], v[212:215], v[28:31]
	v_mfma_f32_16x16x32_bf16 v[20:23], v[154:157], v[220:223], v[20:23]
	v_mfma_f32_16x16x32_bf16 v[12:15], v[172:175], v[220:223], v[12:15]
	v_mfma_f32_16x16x32_bf16 v[64:67], v[168:171], v[200:203], v[64:67]
	v_mfma_f32_16x16x32_bf16 v[60:63], v[176:179], v[200:203], v[60:63]
	v_mfma_f32_16x16x32_bf16 v[52:55], v[168:171], v[208:211], v[52:55]
	v_mfma_f32_16x16x32_bf16 v[44:47], v[176:179], v[208:211], v[44:47]
	v_mfma_f32_16x16x32_bf16 v[36:39], v[168:171], v[216:219], v[36:39]
	v_mfma_f32_16x16x32_bf16 v[28:31], v[176:179], v[216:219], v[28:31]
	v_mfma_f32_16x16x32_bf16 v[20:23], v[168:171], v[224:227], v[20:23]
	v_mfma_f32_16x16x32_bf16 v[12:15], v[176:179], v[224:227], v[12:15]
	s_setprio 0
	s_setprio 1
	v_mfma_f32_16x16x32_bf16 v[56:59], v[180:183], v[196:199], v[56:59]
	v_mfma_f32_16x16x32_bf16 v[48:51], v[188:191], v[196:199], v[48:51]
	v_mfma_f32_16x16x32_bf16 v[40:43], v[180:183], v[204:207], v[40:43]
	v_mfma_f32_16x16x32_bf16 v[32:35], v[188:191], v[204:207], v[32:35]
	v_mfma_f32_16x16x32_bf16 v[24:27], v[180:183], v[212:215], v[24:27]
	v_mfma_f32_16x16x32_bf16 v[16:19], v[188:191], v[212:215], v[16:19]
	v_mfma_f32_16x16x32_bf16 v[8:11], v[180:183], v[220:223], v[8:11]
	v_mfma_f32_16x16x32_bf16 v[4:7], v[188:191], v[220:223], v[4:7]
	v_mfma_f32_16x16x32_bf16 v[56:59], v[184:187], v[200:203], v[56:59]
	v_mfma_f32_16x16x32_bf16 v[48:51], v[192:195], v[200:203], v[48:51]
	v_mfma_f32_16x16x32_bf16 v[40:43], v[184:187], v[208:211], v[40:43]
	v_mfma_f32_16x16x32_bf16 v[32:35], v[192:195], v[208:211], v[32:35]
	v_mfma_f32_16x16x32_bf16 v[24:27], v[184:187], v[216:219], v[24:27]
	v_mfma_f32_16x16x32_bf16 v[16:19], v[192:195], v[216:219], v[16:19]
	v_mfma_f32_16x16x32_bf16 v[8:11], v[184:187], v[224:227], v[8:11]
	v_mfma_f32_16x16x32_bf16 v[4:7], v[192:195], v[224:227], v[4:7]
	s_setprio 0
	s_barrier
	s_add_i32 s35, s35, 2
	s_add_u32 s31, s31, 0x100
	s_addc_u32 s34, s34, 0
	s_add_u32 s44, s44, 0x100
	s_addc_u32 s45, s45, 0
	s_cmp_gt_u32 s35, 29
	s_cbranch_scc0 .LBB0_342
	s_and_b64 vcc, exec, s[22:23]
	s_cbranch_vccz .LBB0_345
	s_barrier

.LBB0_1066:
	s_add_u32 s12, s44, 0xfff80080
	s_addc_u32 s13, s45, -1
	s_add_i32 s14, 0, 0x10000
	s_cmp_eq_u32 s11, 28
	s_cselect_b32 s49, s5, s13
	s_cselect_b32 s48, s6, s12
	s_cselect_b32 s47, s7, s10
	s_cselect_b32 s46, s8, s9
	s_add_i32 s15, 0, 0x14000
	v_add_u32_e32 v154, s14, v163
	v_add_u32_e32 v158, s15, v163
	ds_read_b128 v[142:145], v154
	ds_read_b128 v[146:149], v154 offset:1024
	ds_read_b128 v[150:153], v154 offset:2048
	ds_read_b128 v[154:157], v154 offset:3072
	ds_read_b128 v[168:171], v158
	ds_read_b128 v[172:175], v158 offset:1024
	ds_read_b128 v[176:179], v158 offset:2048
	ds_read_b128 v[180:183], v158 offset:3072
	s_add_i32 m0, s60, 0xc000
	ds_read_b128 v[184:187], v167
	ds_read_b128 v[188:191], v167 offset:1024
	ds_read_b128 v[192:195], v167 offset:2048
	ds_read_b128 v[196:199], v167 offset:3072
	ds_read_b128 v[200:203], v167 offset:4096
	ds_read_b128 v[204:207], v167 offset:5120
	ds_read_b128 v[208:211], v167 offset:6144
	ds_read_b128 v[212:215], v167 offset:7168
	global_load_lds_dwordx4 v140, s[44:45]
	s_add_i32 m0, s60, 0xe000
	s_nop 0
	global_load_lds_dwordx4 v138, s[44:45]
	s_cmp_lg_u32 s32, 0
	s_cbranch_scc1 .Lgu_skip1
	s_waitcnt vmcnt(8)
.Lgu_skip1:
	s_waitcnt lgkmcnt(0)
	s_barrier
	s_setprio 1
	s_waitcnt lgkmcnt(0)
	v_mfma_f32_16x16x32_bf16 v[124:127], v[142:145], v[184:187], v[124:127]
	v_mfma_f32_16x16x32_bf16 v[120:123], v[150:153], v[184:187], v[120:123]
	v_mfma_f32_16x16x32_bf16 v[112:115], v[142:145], v[192:195], v[112:115]
	v_mfma_f32_16x16x32_bf16 v[104:107], v[150:153], v[192:195], v[104:107]
	v_mfma_f32_16x16x32_bf16 v[96:99], v[142:145], v[200:203], v[96:99]
	v_mfma_f32_16x16x32_bf16 v[88:91], v[150:153], v[200:203], v[88:91]
	v_mfma_f32_16x16x32_bf16 v[80:83], v[142:145], v[208:211], v[80:83]
	v_mfma_f32_16x16x32_bf16 v[72:75], v[150:153], v[208:211], v[72:75]
	v_mfma_f32_16x16x32_bf16 v[124:127], v[146:149], v[188:191], v[124:127]
	v_mfma_f32_16x16x32_bf16 v[120:123], v[154:157], v[188:191], v[120:123]
	v_mfma_f32_16x16x32_bf16 v[112:115], v[146:149], v[196:199], v[112:115]
	v_mfma_f32_16x16x32_bf16 v[104:107], v[154:157], v[196:199], v[104:107]
	v_mfma_f32_16x16x32_bf16 v[96:99], v[146:149], v[204:207], v[96:99]
	v_mfma_f32_16x16x32_bf16 v[88:91], v[154:157], v[204:207], v[88:91]
	v_mfma_f32_16x16x32_bf16 v[80:83], v[146:149], v[212:215], v[80:83]
	v_mfma_f32_16x16x32_bf16 v[72:75], v[154:157], v[212:215], v[72:75]
	s_setprio 0
	s_setprio 1
	v_mfma_f32_16x16x32_bf16 v[128:131], v[168:171], v[184:187], v[128:131]
	v_mfma_f32_16x16x32_bf16 v[116:119], v[176:179], v[184:187], v[116:119]
	v_mfma_f32_16x16x32_bf16 v[108:111], v[168:171], v[192:195], v[108:111]
	v_mfma_f32_16x16x32_bf16 v[100:103], v[176:179], v[192:195], v[100:103]
	v_mfma_f32_16x16x32_bf16 v[92:95], v[168:171], v[200:203], v[92:95]
	v_mfma_f32_16x16x32_bf16 v[84:87], v[176:179], v[200:203], v[84:87]
	v_mfma_f32_16x16x32_bf16 v[76:79], v[168:171], v[208:211], v[76:79]
	v_mfma_f32_16x16x32_bf16 v[68:71], v[176:179], v[208:211], v[68:71]
	v_mfma_f32_16x16x32_bf16 v[128:131], v[172:175], v[188:191], v[128:131]
	v_mfma_f32_16x16x32_bf16 v[116:119], v[180:183], v[188:191], v[116:119]
	v_mfma_f32_16x16x32_bf16 v[108:111], v[172:175], v[196:199], v[108:111]
	v_mfma_f32_16x16x32_bf16 v[100:103], v[180:183], v[196:199], v[100:103]
	v_mfma_f32_16x16x32_bf16 v[92:95], v[172:175], v[204:207], v[92:95]
	v_mfma_f32_16x16x32_bf16 v[84:87], v[180:183], v[204:207], v[84:87]
	v_mfma_f32_16x16x32_bf16 v[76:79], v[172:175], v[212:215], v[76:79]
	v_mfma_f32_16x16x32_bf16 v[68:71], v[180:183], v[212:215], v[68:71]
	s_setprio 0
	s_barrier
	s_add_i32 s12, s14, s56
	s_mov_b32 m0, s12
	ds_read_b128 v[184:187], v167 offset:16384
	ds_read_b128 v[188:191], v167 offset:17408
	ds_read_b128 v[192:195], v167 offset:18432
	ds_read_b128 v[196:199], v167 offset:19456
	ds_read_b128 v[200:203], v167 offset:20480
	ds_read_b128 v[204:207], v167 offset:21504
	ds_read_b128 v[208:211], v167 offset:22528
	ds_read_b128 v[212:215], v167 offset:23552
	global_load_lds_dwordx4 v2, s[46:47]
	s_add_i32 m0, s12, 0x2000
	s_add_u32 s12, s46, 0x80000
	s_addc_u32 s13, s47, 0
	s_add_i32 s14, s15, s56
	global_load_lds_dwordx4 v0, s[46:47]
	s_mov_b32 m0, s14
	s_nop 0
	global_load_lds_dwordx4 v2, s[12:13]
	s_add_i32 m0, s14, 0x2000
	s_nop 0
	global_load_lds_dwordx4 v0, s[12:13]
	s_mov_b32 m0, s60
	s_nop 0
	global_load_lds_dwordx4 v134, s[48:49]
	s_mov_b32 m0, s61
	s_nop 0
	global_load_lds_dwordx4 v132, s[48:49]
	s_cmp_lg_u32 s32, 0
	s_cbranch_scc1 .Lgu_skip2
	s_waitcnt vmcnt(8)
.Lgu_skip2:
	s_mov_b32 s32, 0
	s_waitcnt lgkmcnt(0)
	s_barrier
	s_setprio 1
	s_waitcnt lgkmcnt(0)
	v_mfma_f32_16x16x32_bf16 v[64:67], v[142:145], v[184:187], v[64:67]
	v_mfma_f32_16x16x32_bf16 v[56:59], v[150:153], v[184:187], v[56:59]
	v_mfma_f32_16x16x32_bf16 v[48:51], v[142:145], v[192:195], v[48:51]
	v_mfma_f32_16x16x32_bf16 v[40:43], v[150:153], v[192:195], v[40:43]
	v_mfma_f32_16x16x32_bf16 v[32:35], v[142:145], v[200:203], v[32:35]
	v_mfma_f32_16x16x32_bf16 v[24:27], v[150:153], v[200:203], v[24:27]
	v_mfma_f32_16x16x32_bf16 v[16:19], v[142:145], v[208:211], v[16:19]
	v_mfma_f32_16x16x32_bf16 v[8:11], v[150:153], v[208:211], v[8:11]
	v_mfma_f32_16x16x32_bf16 v[64:67], v[146:149], v[188:191], v[64:67]
	v_mfma_f32_16x16x32_bf16 v[56:59], v[154:157], v[188:191], v[56:59]
	v_mfma_f32_16x16x32_bf16 v[48:51], v[146:149], v[196:199], v[48:51]
	v_mfma_f32_16x16x32_bf16 v[40:43], v[154:157], v[196:199], v[40:43]
	v_mfma_f32_16x16x32_bf16 v[32:35], v[146:149], v[204:207], v[32:35]
	v_mfma_f32_16x16x32_bf16 v[24:27], v[154:157], v[204:207], v[24:27]
	v_mfma_f32_16x16x32_bf16 v[16:19], v[146:149], v[212:215], v[16:19]
	v_mfma_f32_16x16x32_bf16 v[8:11], v[154:157], v[212:215], v[8:11]
	s_setprio 0
	s_setprio 1
	v_mfma_f32_16x16x32_bf16 v[60:63], v[168:171], v[184:187], v[60:63]
	v_mfma_f32_16x16x32_bf16 v[52:55], v[176:179], v[184:187], v[52:55]
	v_mfma_f32_16x16x32_bf16 v[44:47], v[168:171], v[192:195], v[44:47]
	v_mfma_f32_16x16x32_bf16 v[36:39], v[176:179], v[192:195], v[36:39]
	v_mfma_f32_16x16x32_bf16 v[28:31], v[168:171], v[200:203], v[28:31]
	v_mfma_f32_16x16x32_bf16 v[20:23], v[176:179], v[200:203], v[20:23]
	v_mfma_f32_16x16x32_bf16 v[12:15], v[168:171], v[208:211], v[12:15]
	v_mfma_f32_16x16x32_bf16 v[4:7], v[176:179], v[208:211], v[4:7]
	v_mfma_f32_16x16x32_bf16 v[60:63], v[172:175], v[188:191], v[60:63]
	v_mfma_f32_16x16x32_bf16 v[52:55], v[180:183], v[188:191], v[52:55]
	v_mfma_f32_16x16x32_bf16 v[44:47], v[172:175], v[196:199], v[44:47]
	v_mfma_f32_16x16x32_bf16 v[36:39], v[180:183], v[196:199], v[36:39]
	v_mfma_f32_16x16x32_bf16 v[28:31], v[172:175], v[204:207], v[28:31]
	v_mfma_f32_16x16x32_bf16 v[20:23], v[180:183], v[204:207], v[20:23]
	v_mfma_f32_16x16x32_bf16 v[12:15], v[172:175], v[212:215], v[12:15]
	v_mfma_f32_16x16x32_bf16 v[4:7], v[180:183], v[212:215], v[4:7]
	s_setprio 0
	s_barrier
	s_add_i32 s14, 0, 0x18000
	s_add_i32 s15, 0, 0x1c000
	v_add_u32_e32 v154, s14, v163
	v_add_u32_e32 v160, s15, v163
	ds_read_b128 v[142:145], v154
	ds_read_b128 v[146:149], v154 offset:1024
	ds_read_b128 v[150:153], v154 offset:2048
	ds_read_b128 v[154:157], v154 offset:3072
	ds_read_b128 v[168:171], v160
	ds_read_b128 v[172:175], v160 offset:1024
	ds_read_b128 v[176:179], v160 offset:2048
	ds_read_b128 v[180:183], v160 offset:3072
	s_add_u32 s12, s48, 0x80000
	s_addc_u32 s13, s49, 0
	s_mov_b32 m0, s62
	ds_read_b128 v[184:187], v167 offset:32768
	ds_read_b128 v[188:191], v167 offset:33792
	ds_read_b128 v[192:195], v167 offset:34816
	ds_read_b128 v[196:199], v167 offset:35840
	ds_read_b128 v[200:203], v167 offset:36864
	ds_read_b128 v[204:207], v167 offset:37888
	ds_read_b128 v[208:211], v167 offset:38912
	ds_read_b128 v[212:215], v167 offset:39936
	global_load_lds_dwordx4 v134, s[12:13]
	s_mov_b32 m0, s63
	s_nop 0
	global_load_lds_dwordx4 v132, s[12:13]
	s_waitcnt vmcnt(8)
	s_waitcnt lgkmcnt(0)
	s_barrier
	s_setprio 1
	s_waitcnt lgkmcnt(0)
	v_mfma_f32_16x16x32_bf16 v[124:127], v[142:145], v[184:187], v[124:127]
	v_mfma_f32_16x16x32_bf16 v[120:123], v[150:153], v[184:187], v[120:123]
	v_mfma_f32_16x16x32_bf16 v[112:115], v[142:145], v[192:195], v[112:115]
	v_mfma_f32_16x16x32_bf16 v[104:107], v[150:153], v[192:195], v[104:107]
	v_mfma_f32_16x16x32_bf16 v[96:99], v[142:145], v[200:203], v[96:99]
	v_mfma_f32_16x16x32_bf16 v[88:91], v[150:153], v[200:203], v[88:91]
	v_mfma_f32_16x16x32_bf16 v[80:83], v[142:145], v[208:211], v[80:83]
	v_mfma_f32_16x16x32_bf16 v[72:75], v[150:153], v[208:211], v[72:75]
	v_mfma_f32_16x16x32_bf16 v[124:127], v[146:149], v[188:191], v[124:127]
	v_mfma_f32_16x16x32_bf16 v[120:123], v[154:157], v[188:191], v[120:123]
	v_mfma_f32_16x16x32_bf16 v[112:115], v[146:149], v[196:199], v[112:115]
	v_mfma_f32_16x16x32_bf16 v[104:107], v[154:157], v[196:199], v[104:107]
	v_mfma_f32_16x16x32_bf16 v[96:99], v[146:149], v[204:207], v[96:99]
	v_mfma_f32_16x16x32_bf16 v[88:91], v[154:157], v[204:207], v[88:91]
	v_mfma_f32_16x16x32_bf16 v[80:83], v[146:149], v[212:215], v[80:83]
	v_mfma_f32_16x16x32_bf16 v[72:75], v[154:157], v[212:215], v[72:75]
	s_setprio 0
	s_setprio 1
	v_mfma_f32_16x16x32_bf16 v[128:131], v[168:171], v[184:187], v[128:131]
	v_mfma_f32_16x16x32_bf16 v[116:119], v[176:179], v[184:187], v[116:119]
	v_mfma_f32_16x16x32_bf16 v[108:111], v[168:171], v[192:195], v[108:111]
	v_mfma_f32_16x16x32_bf16 v[100:103], v[176:179], v[192:195], v[100:103]
	v_mfma_f32_16x16x32_bf16 v[92:95], v[168:171], v[200:203], v[92:95]
	v_mfma_f32_16x16x32_bf16 v[84:87], v[176:179], v[200:203], v[84:87]
	v_mfma_f32_16x16x32_bf16 v[76:79], v[168:171], v[208:211], v[76:79]
	v_mfma_f32_16x16x32_bf16 v[68:71], v[176:179], v[208:211], v[68:71]
	v_mfma_f32_16x16x32_bf16 v[128:131], v[172:175], v[188:191], v[128:131]
	v_mfma_f32_16x16x32_bf16 v[116:119], v[180:183], v[188:191], v[116:119]
	v_mfma_f32_16x16x32_bf16 v[108:111], v[172:175], v[196:199], v[108:111]
	v_mfma_f32_16x16x32_bf16 v[100:103], v[180:183], v[196:199], v[100:103]
	v_mfma_f32_16x16x32_bf16 v[92:95], v[172:175], v[204:207], v[92:95]
	v_mfma_f32_16x16x32_bf16 v[84:87], v[180:183], v[204:207], v[84:87]
	v_mfma_f32_16x16x32_bf16 v[76:79], v[172:175], v[212:215], v[76:79]
	v_mfma_f32_16x16x32_bf16 v[68:71], v[180:183], v[212:215], v[68:71]
	s_setprio 0
	s_barrier
	s_add_i32 s12, s14, s56
	s_mov_b32 m0, s12
	ds_read_b128 v[184:187], v167 offset:49152
	ds_read_b128 v[188:191], v167 offset:50176
	ds_read_b128 v[192:195], v167 offset:51200
	ds_read_b128 v[196:199], v167 offset:52224
	ds_read_b128 v[200:203], v167 offset:53248
	ds_read_b128 v[204:207], v167 offset:54272
	ds_read_b128 v[208:211], v167 offset:55296
	ds_read_b128 v[212:215], v167 offset:56320
	s_add_u32 s100, s46, 0x80
	s_addc_u32 s101, s47, 0
	global_load_lds_dwordx4 v2, s[100:101]
	s_add_i32 m0, s12, 0x2000
	s_add_u32 s12, s46, 0x80080
	s_addc_u32 s13, s47, 0
	s_add_i32 s14, s15, s56
	s_add_u32 s100, s46, 0x80
	s_addc_u32 s101, s47, 0
	global_load_lds_dwordx4 v0, s[100:101]
	s_mov_b32 m0, s14
	s_nop 0
	global_load_lds_dwordx4 v2, s[12:13]
	s_add_i32 m0, s14, 0x2000
	s_nop 0
	global_load_lds_dwordx4 v0, s[12:13]
	s_mov_b32 m0, s64
	s_nop 0
	s_add_u32 s100, s48, 0x80
	s_addc_u32 s101, s49, 0
	global_load_lds_dwordx4 v134, s[100:101]
	s_mov_b32 m0, s65
	s_nop 0
	s_add_u32 s100, s48, 0x80
	s_addc_u32 s101, s49, 0
	global_load_lds_dwordx4 v132, s[100:101]
	s_waitcnt vmcnt(8)
	s_waitcnt lgkmcnt(0)
	s_barrier
	s_setprio 1
	s_waitcnt lgkmcnt(0)
	v_mfma_f32_16x16x32_bf16 v[64:67], v[142:145], v[184:187], v[64:67]
	v_mfma_f32_16x16x32_bf16 v[56:59], v[150:153], v[184:187], v[56:59]
	v_mfma_f32_16x16x32_bf16 v[48:51], v[142:145], v[192:195], v[48:51]
	v_mfma_f32_16x16x32_bf16 v[40:43], v[150:153], v[192:195], v[40:43]
	v_mfma_f32_16x16x32_bf16 v[32:35], v[142:145], v[200:203], v[32:35]
	v_mfma_f32_16x16x32_bf16 v[24:27], v[150:153], v[200:203], v[24:27]
	v_mfma_f32_16x16x32_bf16 v[16:19], v[142:145], v[208:211], v[16:19]
	v_mfma_f32_16x16x32_bf16 v[8:11], v[150:153], v[208:211], v[8:11]
	v_mfma_f32_16x16x32_bf16 v[64:67], v[146:149], v[188:191], v[64:67]
	v_mfma_f32_16x16x32_bf16 v[56:59], v[154:157], v[188:191], v[56:59]
	v_mfma_f32_16x16x32_bf16 v[48:51], v[146:149], v[196:199], v[48:51]
	v_mfma_f32_16x16x32_bf16 v[40:43], v[154:157], v[196:199], v[40:43]
	v_mfma_f32_16x16x32_bf16 v[32:35], v[146:149], v[204:207], v[32:35]
	v_mfma_f32_16x16x32_bf16 v[24:27], v[154:157], v[204:207], v[24:27]
	v_mfma_f32_16x16x32_bf16 v[16:19], v[146:149], v[212:215], v[16:19]
	v_mfma_f32_16x16x32_bf16 v[8:11], v[154:157], v[212:215], v[8:11]
	s_setprio 0
	s_setprio 1
	v_mfma_f32_16x16x32_bf16 v[60:63], v[168:171], v[184:187], v[60:63]
	v_mfma_f32_16x16x32_bf16 v[52:55], v[176:179], v[184:187], v[52:55]
	v_mfma_f32_16x16x32_bf16 v[44:47], v[168:171], v[192:195], v[44:47]
	v_mfma_f32_16x16x32_bf16 v[36:39], v[176:179], v[192:195], v[36:39]
	v_mfma_f32_16x16x32_bf16 v[28:31], v[168:171], v[200:203], v[28:31]
	v_mfma_f32_16x16x32_bf16 v[20:23], v[176:179], v[200:203], v[20:23]
	v_mfma_f32_16x16x32_bf16 v[12:15], v[168:171], v[208:211], v[12:15]
	v_mfma_f32_16x16x32_bf16 v[4:7], v[176:179], v[208:211], v[4:7]
	v_mfma_f32_16x16x32_bf16 v[60:63], v[172:175], v[188:191], v[60:63]
	v_mfma_f32_16x16x32_bf16 v[52:55], v[180:183], v[188:191], v[52:55]
	v_mfma_f32_16x16x32_bf16 v[44:47], v[172:175], v[196:199], v[44:47]
	v_mfma_f32_16x16x32_bf16 v[36:39], v[180:183], v[196:199], v[36:39]
	v_mfma_f32_16x16x32_bf16 v[28:31], v[172:175], v[204:207], v[28:31]
	v_mfma_f32_16x16x32_bf16 v[20:23], v[180:183], v[204:207], v[20:23]
	v_mfma_f32_16x16x32_bf16 v[12:15], v[172:175], v[212:215], v[12:15]
	v_mfma_f32_16x16x32_bf16 v[4:7], v[180:183], v[212:215], v[4:7]
	s_setprio 0
	s_barrier
	s_add_i32 s11, s11, 2
	s_add_u32 s9, s9, 0x100
	s_addc_u32 s10, s10, 0
	s_add_u32 s44, s44, 0x100
	s_addc_u32 s45, s45, 0
	s_cmp_gt_u32 s11, 29
	s_cbranch_scc0 .LBB0_1066
	s_and_b64 vcc, exec, s[22:23]
	s_cbranch_vccz .LBB0_1069
	s_barrier

	.amdhsa_kernel _Z5k_fwd6Params
		.amdhsa_group_segment_fixed_size 0
		.amdhsa_private_segment_fixed_size 0
		.amdhsa_kernarg_size 384
		.amdhsa_user_sgpr_count 2
		.amdhsa_user_sgpr_dispatch_ptr 0
		.amdhsa_user_sgpr_queue_ptr 0
		.amdhsa_user_sgpr_kernarg_segment_ptr 1
		.amdhsa_user_sgpr_dispatch_id 0
		.amdhsa_user_sgpr_kernarg_preload_length 0
		.amdhsa_user_sgpr_kernarg_preload_offset 0
		.amdhsa_user_sgpr_private_segment_size 0
		.amdhsa_uses_dynamic_stack 0
		.amdhsa_enable_private_segment 0
		.amdhsa_system_sgpr_workgroup_id_x 1
		.amdhsa_system_sgpr_workgroup_id_y 0
		.amdhsa_system_sgpr_workgroup_id_z 0
		.amdhsa_system_sgpr_workgroup_info 0
		.amdhsa_system_vgpr_workitem_id 0
		.amdhsa_next_free_vgpr 256
		.amdhsa_next_free_sgpr 102
		.amdhsa_accum_offset 256
		.amdhsa_reserve_vcc 1
		.amdhsa_float_round_mode_32 0
		.amdhsa_float_round_mode_16_64 0
		.amdhsa_float_denorm_mode_32 3
		.amdhsa_float_denorm_mode_16_64 3
		.amdhsa_dx10_clamp 1
		.amdhsa_ieee_mode 1
		.amdhsa_fp16_overflow 0
		.amdhsa_tg_split 0
		.amdhsa_exception_fp_ieee_invalid_op 0
		.amdhsa_exception_fp_denorm_src 0
		.amdhsa_exception_fp_ieee_div_zero 0
		.amdhsa_exception_fp_ieee_overflow 0
		.amdhsa_exception_fp_ieee_underflow 0
		.amdhsa_exception_fp_ieee_inexact 0
		.amdhsa_exception_int_div_zero 0
	.end_amdhsa_kernel

amdhsa.kernels:
  - .agpr_count:     0
    .args:
      - .offset:         0
        .size:           128
        .value_kind:     by_value
      - .offset:         128
        .size:           4
        .value_kind:     hidden_block_count_x
      - .offset:         132
        .size:           4
        .value_kind:     hidden_block_count_y
      - .offset:         136
        .size:           4
        .value_kind:     hidden_block_count_z
      - .offset:         140
        .size:           2
        .value_kind:     hidden_group_size_x
      - .offset:         142
        .size:           2
        .value_kind:     hidden_group_size_y
      - .offset:         144
        .size:           2
        .value_kind:     hidden_group_size_z
      - .offset:         146
        .size:           2
        .value_kind:     hidden_remainder_x
      - .offset:         148
        .size:           2
        .value_kind:     hidden_remainder_y
      - .offset:         150
        .size:           2
        .value_kind:     hidden_remainder_z
      - .offset:         168
        .size:           8
        .value_kind:     hidden_global_offset_x
      - .offset:         176
        .size:           8
        .value_kind:     hidden_global_offset_y
      - .offset:         184
        .size:           8
        .value_kind:     hidden_global_offset_z
      - .offset:         192
        .size:           2
        .value_kind:     hidden_grid_dims
      - .offset:         248
        .size:           4
        .value_kind:     hidden_dynamic_lds_size
    .group_segment_fixed_size: 0
    .kernarg_segment_align: 8
    .kernarg_segment_size: 384
    .language:       OpenCL C
    .language_version:
      - 2
      - 0
    .max_flat_workgroup_size: 512
    .name:           _Z5k_fwd6Params
    .private_segment_fixed_size: 0
    .sgpr_count:     108
    .sgpr_spill_count: 165
    .symbol:         _Z5k_fwd6Params.kd
    .uniform_work_group_size: 1
    .uses_dynamic_stack: false
    .vgpr_count:     256
    .vgpr_spill_count: 0
    .wavefront_size: 64
